# GEMM MFMA order: same-accumulator k0/k1 pairs adjacent, plus early barrier
# speedup vs baseline: 1.0074x; 1.0074x over previous
; #define PG8_STAGE(bufoff, gbase, voff) do { _Pragma("unroll") for (int _i = 0; _i < 2; ++_i) \
;         __builtin_amdgcn_global_load_lds((const unsigned*)((const char*)(gbase) + (voff)[_i]), (PG8_LAS unsigned*)(lds + (bufoff) + ldsw + _i * 8192), 16, 0, 0); } while (0)
; #define PG8_LDA(dst, b, h) do { _Pragma("unroll") for (int m = 0; m < 4; ++m) _Pragma("unroll") for (int k = 0; k < 2; ++k) dst[m][k] = *(const PG8_LAS bf16x8*)(lds + PG8_SA(b, h) + aoff + m * 2048 + k * 1024); } while (0)
; #define PG8_LDB(dst, b, h) do { _Pragma("unroll") for (int n = 0; n < 2; ++n) _Pragma("unroll") for (int k = 0; k < 2; ++k) dst[n][k] = *(const PG8_LAS bf16x8*)(lds + PG8_SB(b, h) + boff + n * 2048 + k * 1024); } while (0)
; #define PG8_WAIT_V(n) asm volatile("s_waitcnt vmcnt(" #n ")" ::: "memory")
; #define PG8_WAIT_L(n) asm volatile("s_waitcnt lgkmcnt(" #n ")" ::: "memory")
; #define PG8_BAR __builtin_amdgcn_s_barrier()
; #define PG8_SCHED __builtin_amdgcn_sched_barrier(0)
; template <class Epi, class Sched, bool ALIGN_EPI = false, bool SP2 = false>
; __device__ __forceinline__ void gemm_phase(PG8_LAS unsigned char* lds, const Gemm g, const Sched& S, const Epi& E) {
;     ...
;         const char* nA = has_next ? (const char*)g.A + (size_t)nxt.pm * tstep : cA; const char* nB = has_next ? (const char*)g.Bt + (size_t)nxt.pn * tstep : cB;
;         for (int t = 0; t < nt; t += 2) {
;             const bool last = (t == nt - 2);
;             const char* a1 = cA + (size_t)(t + 1) * kstepB;
;             const char* a2 = last ? nA : cA + (size_t)(t + 2) * kstepB; const char* b2 = last ? nB : cB + (size_t)(t + 2) * kstepB;
;             const char* a3 = a2 + kstepB; const char* b3 = b2 + kstepB;
;             if (last && has_next) S.a_ready(nxt);
;             if constexpr (SP2) {
;             PG8_LDB(B0, 0, 0); PG8_LDB(B1, 0, 1); PG8_SCHED; PG8_LDA(At, 0, 0); PG8_STAGE(PG8_SA(1, 1), a1 + hstepB, voffA);
;             PG8_WAIT_V(8); PG8_WAIT_L(0); PG8_BAR; PG8_MMA(0, 0, At, B0); PG8_MMA(0, 1, At, B1); PG8_BAR; PG8_SCHED;
;             PG8_LDA(At, 0, 1); PG8_STAGE(PG8_SB(0, 0), b2, voffB); PG8_STAGE(PG8_SB(0, 1), b2 + hstepB, voffB); PG8_STAGE(PG8_SA(0, 0), a2, voffA);
;             PG8_WAIT_V(8); PG8_WAIT_L(0); PG8_BAR; PG8_MMA(1, 0, At, B0); PG8_MMA(1, 1, At, B1); PG8_BAR; PG8_SCHED;
.LBB0_193:
	s_add_i32 s84, s38, 2
	s_add_u32 s39, s36, 0x4000
	s_addc_u32 s40, s37, 0
	s_cmp_eq_u32 s31, s38
	s_cselect_b32 s42, s8, s39
	s_cselect_b32 s43, s9, s40
	s_cselect_b32 s40, s62, s78
	s_cselect_b32 s41, s63, s82
	s_add_u32 s38, s42, 0x8000
	s_addc_u32 s39, s43, 0
	s_add_i32 s90, 0, 0x10000
	s_add_i32 s64, 0, 0x14000
	v_add_u32_e32 v140, s90, v174
	v_add_u32_e32 v161, s64, v174
	ds_read_b128 v[128:131], v140
	ds_read_b128 v[132:135], v140 offset:1024
	ds_read_b128 v[136:139], v140 offset:2048
	ds_read_b128 v[140:143], v140 offset:3072
	ds_read_b128 v[144:147], v161
	ds_read_b128 v[148:151], v161 offset:1024
	ds_read_b128 v[178:181], v161 offset:2048
	ds_read_b128 v[182:185], v161 offset:3072
	v_lshl_add_u64 v[172:173], s[36:37], 0, v[168:169]
	s_add_i32 m0, s21, 0xc000
	ds_read_b128 v[186:189], v177
	ds_read_b128 v[190:193], v177 offset:1024
	ds_read_b128 v[194:197], v177 offset:2048
	ds_read_b128 v[198:201], v177 offset:3072
	ds_read_b128 v[202:205], v177 offset:4096
	ds_read_b128 v[206:209], v177 offset:5120
	ds_read_b128 v[210:213], v177 offset:6144
	ds_read_b128 v[214:217], v177 offset:7168
	global_load_lds_dwordx4 v[172:173], off
	v_lshl_add_u64 v[172:173], s[36:37], 0, v[170:171]
	s_add_i32 m0, s21, 0xe000
	s_nop 0
	global_load_lds_dwordx4 v[172:173], off
	s_waitcnt vmcnt(8)
	s_waitcnt lgkmcnt(0)
	s_barrier
	s_setprio 1
	s_waitcnt lgkmcnt(0)
	v_mfma_f32_16x16x32_bf16 v[124:127], v[128:131], v[186:189], v[124:127]
	v_mfma_f32_16x16x32_bf16 v[124:127], v[132:135], v[190:193], v[124:127]
	v_mfma_f32_16x16x32_bf16 v[120:123], v[136:139], v[186:189], v[120:123]
	v_mfma_f32_16x16x32_bf16 v[120:123], v[140:143], v[190:193], v[120:123]
	v_mfma_f32_16x16x32_bf16 v[108:111], v[128:131], v[194:197], v[108:111]
	v_mfma_f32_16x16x32_bf16 v[108:111], v[132:135], v[198:201], v[108:111]
	v_mfma_f32_16x16x32_bf16 v[104:107], v[136:139], v[194:197], v[104:107]
	v_mfma_f32_16x16x32_bf16 v[104:107], v[140:143], v[198:201], v[104:107]
	v_mfma_f32_16x16x32_bf16 v[92:95], v[128:131], v[202:205], v[92:95]
	v_mfma_f32_16x16x32_bf16 v[92:95], v[132:135], v[206:209], v[92:95]
	v_mfma_f32_16x16x32_bf16 v[88:91], v[136:139], v[202:205], v[88:91]
	v_mfma_f32_16x16x32_bf16 v[88:91], v[140:143], v[206:209], v[88:91]
	v_mfma_f32_16x16x32_bf16 v[76:79], v[128:131], v[210:213], v[76:79]
	v_mfma_f32_16x16x32_bf16 v[76:79], v[132:135], v[214:217], v[76:79]
	v_mfma_f32_16x16x32_bf16 v[72:75], v[136:139], v[210:213], v[72:75]
	v_mfma_f32_16x16x32_bf16 v[72:75], v[140:143], v[214:217], v[72:75]
	s_setprio 0
	s_setprio 1
	v_mfma_f32_16x16x32_bf16 v[116:119], v[144:147], v[186:189], v[116:119]
	v_mfma_f32_16x16x32_bf16 v[116:119], v[148:151], v[190:193], v[116:119]
	v_mfma_f32_16x16x32_bf16 v[112:115], v[178:181], v[186:189], v[112:115]
	v_mfma_f32_16x16x32_bf16 v[112:115], v[182:185], v[190:193], v[112:115]
	v_mfma_f32_16x16x32_bf16 v[100:103], v[144:147], v[194:197], v[100:103]
	v_mfma_f32_16x16x32_bf16 v[100:103], v[148:151], v[198:201], v[100:103]
	v_mfma_f32_16x16x32_bf16 v[96:99], v[178:181], v[194:197], v[96:99]
	v_mfma_f32_16x16x32_bf16 v[96:99], v[182:185], v[198:201], v[96:99]
	v_mfma_f32_16x16x32_bf16 v[84:87], v[144:147], v[202:205], v[84:87]
	v_mfma_f32_16x16x32_bf16 v[84:87], v[148:151], v[206:209], v[84:87]
	v_mfma_f32_16x16x32_bf16 v[80:83], v[178:181], v[202:205], v[80:83]
	v_mfma_f32_16x16x32_bf16 v[80:83], v[182:185], v[206:209], v[80:83]
	s_setprio 2
	s_barrier
	v_mfma_f32_16x16x32_bf16 v[68:71], v[144:147], v[210:213], v[68:71]
	v_mfma_f32_16x16x32_bf16 v[68:71], v[148:151], v[214:217], v[68:71]
	v_mfma_f32_16x16x32_bf16 v[64:67], v[178:181], v[210:213], v[64:67]
	v_mfma_f32_16x16x32_bf16 v[64:67], v[182:185], v[214:217], v[64:67]
	s_setprio 0
	s_add_i32 s65, s90, s20
	v_lshl_add_u64 v[172:173], s[40:41], 0, v[156:157]
	s_mov_b32 m0, s65
	ds_read_b128 v[186:189], v177 offset:16384
	ds_read_b128 v[190:193], v177 offset:17408
	ds_read_b128 v[194:197], v177 offset:18432
	ds_read_b128 v[198:201], v177 offset:19456
	ds_read_b128 v[202:205], v177 offset:20480
	ds_read_b128 v[206:209], v177 offset:21504
	ds_read_b128 v[210:213], v177 offset:22528
	ds_read_b128 v[214:217], v177 offset:23552
	global_load_lds_dwordx4 v[172:173], off
	s_add_i32 m0, s65, 0x2000
	s_add_u32 vcc_lo, s40, 0x4000
	v_lshl_add_u64 v[172:173], s[40:41], 0, v[152:153]
	s_addc_u32 vcc_hi, s41, 0
	s_add_i32 s64, s64, s20
	global_load_lds_dwordx4 v[172:173], off
	v_lshl_add_u64 v[172:173], vcc, 0, v[156:157]
	s_mov_b32 m0, s64
	s_nop 0
	global_load_lds_dwordx4 v[172:173], off
	v_lshl_add_u64 v[172:173], vcc, 0, v[152:153]
	s_add_i32 m0, s64, 0x2000
	s_nop 0
	global_load_lds_dwordx4 v[172:173], off
	v_lshl_add_u64 v[172:173], s[42:43], 0, v[158:159]
	s_mov_b32 m0, s21
	s_nop 0
	global_load_lds_dwordx4 v[172:173], off
	v_lshl_add_u64 v[172:173], s[42:43], 0, v[154:155]
	s_mov_b32 m0, s22
	s_nop 0
	global_load_lds_dwordx4 v[172:173], off
	s_waitcnt vmcnt(8)
	s_waitcnt lgkmcnt(0)
	s_barrier
; #define PG8_STAGE(bufoff, gbase, voff) do { _Pragma("unroll") for (int _i = 0; _i < 2; ++_i) \
;         __builtin_amdgcn_global_load_lds((const unsigned*)((const char*)(gbase) + (voff)[_i]), (PG8_LAS unsigned*)(lds + (bufoff) + ldsw + _i * 8192), 16, 0, 0); } while (0)
; #define PG8_LDA(dst, b, h) do { _Pragma("unroll") for (int m = 0; m < 4; ++m) _Pragma("unroll") for (int k = 0; k < 2; ++k) dst[m][k] = *(const PG8_LAS bf16x8*)(lds + PG8_SA(b, h) + aoff + m * 2048 + k * 1024); } while (0)
; #define PG8_LDB(dst, b, h) do { _Pragma("unroll") for (int n = 0; n < 2; ++n) _Pragma("unroll") for (int k = 0; k < 2; ++k) dst[n][k] = *(const PG8_LAS bf16x8*)(lds + PG8_SB(b, h) + boff + n * 2048 + k * 1024); } while (0)
; #define PG8_MMA(ai, bj, At, Bt) do { __builtin_amdgcn_s_setprio(1); _Pragma("unroll") for (int m = 0; m < 4; ++m) _Pragma("unroll") for (int n = 0; n < 2; ++n) _Pragma("unroll") for (int k = 0; k < 2; ++k) \
;         acc[ai][bj][m][n] = __builtin_amdgcn_mfma_f32_16x16x32_bf16(Bt[n][k], At[m][k], acc[ai][bj][m][n], 0, 0, 0); __builtin_amdgcn_s_setprio(0); } while (0)
; #define PG8_WAIT_V(n) asm volatile("s_waitcnt vmcnt(" #n ")" ::: "memory")
; #define PG8_WAIT_L(n) asm volatile("s_waitcnt lgkmcnt(" #n ")" ::: "memory")
; #define PG8_BAR __builtin_amdgcn_s_barrier()
; #define PG8_SCHED __builtin_amdgcn_sched_barrier(0)
; template <class Epi, class Sched, bool ALIGN_EPI = false, bool SP2 = false>
; __device__ __forceinline__ void gemm_phase(PG8_LAS unsigned char* lds, const Gemm g, const Sched& S, const Epi& E) {
;     ...
;             PG8_WAIT_V(8); PG8_WAIT_L(0); PG8_BAR; PG8_MMA(1, 0, At, B0); PG8_MMA(1, 1, At, B1); PG8_BAR; PG8_SCHED;
;             PG8_LDB(B0, 1, 0); PG8_LDB(B1, 1, 1); PG8_SCHED; PG8_LDA(At, 1, 0); PG8_STAGE(PG8_SA(0, 1), a2 + hstepB, voffA);
;             PG8_WAIT_V(8); PG8_WAIT_L(0); PG8_BAR; PG8_MMA(0, 0, At, B0); PG8_MMA(0, 1, At, B1); PG8_BAR; PG8_SCHED;
;             PG8_LDA(At, 1, 1); PG8_STAGE(PG8_SB(1, 0), b3, voffB); PG8_STAGE(PG8_SB(1, 1), b3 + hstepB, voffB); PG8_STAGE(PG8_SA(1, 0), a3, voffA);
	s_setprio 1
	s_waitcnt lgkmcnt(0)
	v_mfma_f32_16x16x32_bf16 v[60:63], v[128:131], v[186:189], v[60:63]
	v_mfma_f32_16x16x32_bf16 v[60:63], v[132:135], v[190:193], v[60:63]
	v_mfma_f32_16x16x32_bf16 v[56:59], v[136:139], v[186:189], v[56:59]
	v_mfma_f32_16x16x32_bf16 v[56:59], v[140:143], v[190:193], v[56:59]
	v_mfma_f32_16x16x32_bf16 v[44:47], v[128:131], v[194:197], v[44:47]
	v_mfma_f32_16x16x32_bf16 v[44:47], v[132:135], v[198:201], v[44:47]
	v_mfma_f32_16x16x32_bf16 v[40:43], v[136:139], v[194:197], v[40:43]
	v_mfma_f32_16x16x32_bf16 v[40:43], v[140:143], v[198:201], v[40:43]
	v_mfma_f32_16x16x32_bf16 v[28:31], v[128:131], v[202:205], v[28:31]
	v_mfma_f32_16x16x32_bf16 v[28:31], v[132:135], v[206:209], v[28:31]
	v_mfma_f32_16x16x32_bf16 v[24:27], v[136:139], v[202:205], v[24:27]
	v_mfma_f32_16x16x32_bf16 v[24:27], v[140:143], v[206:209], v[24:27]
	v_mfma_f32_16x16x32_bf16 v[12:15], v[128:131], v[210:213], v[12:15]
	v_mfma_f32_16x16x32_bf16 v[12:15], v[132:135], v[214:217], v[12:15]
	v_mfma_f32_16x16x32_bf16 v[8:11], v[136:139], v[210:213], v[8:11]
	v_mfma_f32_16x16x32_bf16 v[8:11], v[140:143], v[214:217], v[8:11]
	s_setprio 0
	s_setprio 1
	v_mfma_f32_16x16x32_bf16 v[52:55], v[144:147], v[186:189], v[52:55]
	v_mfma_f32_16x16x32_bf16 v[52:55], v[148:151], v[190:193], v[52:55]
	v_mfma_f32_16x16x32_bf16 v[48:51], v[178:181], v[186:189], v[48:51]
	v_mfma_f32_16x16x32_bf16 v[48:51], v[182:185], v[190:193], v[48:51]
	v_mfma_f32_16x16x32_bf16 v[36:39], v[144:147], v[194:197], v[36:39]
	v_mfma_f32_16x16x32_bf16 v[36:39], v[148:151], v[198:201], v[36:39]
	v_mfma_f32_16x16x32_bf16 v[32:35], v[178:181], v[194:197], v[32:35]
	v_mfma_f32_16x16x32_bf16 v[32:35], v[182:185], v[198:201], v[32:35]
	v_mfma_f32_16x16x32_bf16 v[20:23], v[144:147], v[202:205], v[20:23]
	v_mfma_f32_16x16x32_bf16 v[20:23], v[148:151], v[206:209], v[20:23]
	v_mfma_f32_16x16x32_bf16 v[16:19], v[178:181], v[202:205], v[16:19]
	v_mfma_f32_16x16x32_bf16 v[16:19], v[182:185], v[206:209], v[16:19]
	s_setprio 2
	s_barrier
	v_mfma_f32_16x16x32_bf16 v[4:7], v[144:147], v[210:213], v[4:7]
	v_mfma_f32_16x16x32_bf16 v[4:7], v[148:151], v[214:217], v[4:7]
	v_mfma_f32_16x16x32_bf16 v[0:3], v[178:181], v[210:213], v[0:3]
	v_mfma_f32_16x16x32_bf16 v[0:3], v[182:185], v[214:217], v[0:3]
	s_setprio 0
	s_add_i32 s64, 0, 0x18000
	s_add_i32 s65, 0, 0x1c000
	v_add_u32_e32 v140, s64, v174
	v_add_u32_e32 v161, s65, v174
	ds_read_b128 v[128:131], v140
	ds_read_b128 v[132:135], v140 offset:1024
	ds_read_b128 v[136:139], v140 offset:2048
	ds_read_b128 v[140:143], v140 offset:3072
	ds_read_b128 v[144:147], v161
	ds_read_b128 v[148:151], v161 offset:1024
	ds_read_b128 v[178:181], v161 offset:2048
	ds_read_b128 v[182:185], v161 offset:3072
	s_add_u32 s42, s42, 0x4000
	s_addc_u32 s43, s43, 0
	s_mov_b32 m0, s23
	v_lshl_add_u64 v[172:173], s[42:43], 0, v[158:159]
	ds_read_b128 v[186:189], v177 offset:32768
	ds_read_b128 v[190:193], v177 offset:33792
	ds_read_b128 v[194:197], v177 offset:34816
	ds_read_b128 v[198:201], v177 offset:35840
	ds_read_b128 v[202:205], v177 offset:36864
	ds_read_b128 v[206:209], v177 offset:37888
	ds_read_b128 v[210:213], v177 offset:38912
	ds_read_b128 v[214:217], v177 offset:39936
	global_load_lds_dwordx4 v[172:173], off
	v_lshl_add_u64 v[172:173], s[42:43], 0, v[154:155]
	s_mov_b32 m0, s24
	s_nop 0
	global_load_lds_dwordx4 v[172:173], off
	s_waitcnt vmcnt(8)
	s_waitcnt lgkmcnt(0)
	s_barrier
	s_setprio 1
	s_waitcnt lgkmcnt(0)
	v_mfma_f32_16x16x32_bf16 v[124:127], v[128:131], v[186:189], v[124:127]
	v_mfma_f32_16x16x32_bf16 v[124:127], v[132:135], v[190:193], v[124:127]
	v_mfma_f32_16x16x32_bf16 v[120:123], v[136:139], v[186:189], v[120:123]
	v_mfma_f32_16x16x32_bf16 v[120:123], v[140:143], v[190:193], v[120:123]
	v_mfma_f32_16x16x32_bf16 v[108:111], v[128:131], v[194:197], v[108:111]
	v_mfma_f32_16x16x32_bf16 v[108:111], v[132:135], v[198:201], v[108:111]
	v_mfma_f32_16x16x32_bf16 v[104:107], v[136:139], v[194:197], v[104:107]
	v_mfma_f32_16x16x32_bf16 v[104:107], v[140:143], v[198:201], v[104:107]
	v_mfma_f32_16x16x32_bf16 v[92:95], v[128:131], v[202:205], v[92:95]
	v_mfma_f32_16x16x32_bf16 v[92:95], v[132:135], v[206:209], v[92:95]
	v_mfma_f32_16x16x32_bf16 v[88:91], v[136:139], v[202:205], v[88:91]
	v_mfma_f32_16x16x32_bf16 v[88:91], v[140:143], v[206:209], v[88:91]
	v_mfma_f32_16x16x32_bf16 v[76:79], v[128:131], v[210:213], v[76:79]
	v_mfma_f32_16x16x32_bf16 v[76:79], v[132:135], v[214:217], v[76:79]
	v_mfma_f32_16x16x32_bf16 v[72:75], v[136:139], v[210:213], v[72:75]
	v_mfma_f32_16x16x32_bf16 v[72:75], v[140:143], v[214:217], v[72:75]
	s_setprio 0
	s_setprio 1
	v_mfma_f32_16x16x32_bf16 v[116:119], v[144:147], v[186:189], v[116:119]
	v_mfma_f32_16x16x32_bf16 v[116:119], v[148:151], v[190:193], v[116:119]
	v_mfma_f32_16x16x32_bf16 v[112:115], v[178:181], v[186:189], v[112:115]
	v_mfma_f32_16x16x32_bf16 v[112:115], v[182:185], v[190:193], v[112:115]
	v_mfma_f32_16x16x32_bf16 v[100:103], v[144:147], v[194:197], v[100:103]
	v_mfma_f32_16x16x32_bf16 v[100:103], v[148:151], v[198:201], v[100:103]
	v_mfma_f32_16x16x32_bf16 v[96:99], v[178:181], v[194:197], v[96:99]
	v_mfma_f32_16x16x32_bf16 v[96:99], v[182:185], v[198:201], v[96:99]
	v_mfma_f32_16x16x32_bf16 v[84:87], v[144:147], v[202:205], v[84:87]
	v_mfma_f32_16x16x32_bf16 v[84:87], v[148:151], v[206:209], v[84:87]
	v_mfma_f32_16x16x32_bf16 v[80:83], v[178:181], v[202:205], v[80:83]
	v_mfma_f32_16x16x32_bf16 v[80:83], v[182:185], v[206:209], v[80:83]
	s_setprio 2
	s_barrier
; #define PG8_STAGE(bufoff, gbase, voff) do { _Pragma("unroll") for (int _i = 0; _i < 2; ++_i) \
;         __builtin_amdgcn_global_load_lds((const unsigned*)((const char*)(gbase) + (voff)[_i]), (PG8_LAS unsigned*)(lds + (bufoff) + ldsw + _i * 8192), 16, 0, 0); } while (0)
; #define PG8_LDA(dst, b, h) do { _Pragma("unroll") for (int m = 0; m < 4; ++m) _Pragma("unroll") for (int k = 0; k < 2; ++k) dst[m][k] = *(const PG8_LAS bf16x8*)(lds + PG8_SA(b, h) + aoff + m * 2048 + k * 1024); } while (0)
; #define PG8_MMA(ai, bj, At, Bt) do { __builtin_amdgcn_s_setprio(1); _Pragma("unroll") for (int m = 0; m < 4; ++m) _Pragma("unroll") for (int n = 0; n < 2; ++n) _Pragma("unroll") for (int k = 0; k < 2; ++k) \
;         acc[ai][bj][m][n] = __builtin_amdgcn_mfma_f32_16x16x32_bf16(Bt[n][k], At[m][k], acc[ai][bj][m][n], 0, 0, 0); __builtin_amdgcn_s_setprio(0); } while (0)
; #define PG8_WAIT_V(n) asm volatile("s_waitcnt vmcnt(" #n ")" ::: "memory")
; #define PG8_WAIT_L(n) asm volatile("s_waitcnt lgkmcnt(" #n ")" ::: "memory")
; #define PG8_BAR __builtin_amdgcn_s_barrier()
; #define PG8_SCHED __builtin_amdgcn_sched_barrier(0)
; template <class Epi, class Sched, bool ALIGN_EPI = false, bool SP2 = false>
; __device__ __forceinline__ void gemm_phase(PG8_LAS unsigned char* lds, const Gemm g, const Sched& S, const Epi& E) {
;     ...
;             PG8_LDA(At, 1, 1); PG8_STAGE(PG8_SB(1, 0), b3, voffB); PG8_STAGE(PG8_SB(1, 1), b3 + hstepB, voffB); PG8_STAGE(PG8_SA(1, 0), a3, voffA);
;             PG8_WAIT_V(8); PG8_WAIT_L(0); PG8_BAR; PG8_MMA(1, 0, At, B0); PG8_MMA(1, 1, At, B1); PG8_BAR; PG8_SCHED;
	v_mfma_f32_16x16x32_bf16 v[68:71], v[144:147], v[210:213], v[68:71]
	v_mfma_f32_16x16x32_bf16 v[68:71], v[148:151], v[214:217], v[68:71]
	v_mfma_f32_16x16x32_bf16 v[64:67], v[178:181], v[210:213], v[64:67]
	v_mfma_f32_16x16x32_bf16 v[64:67], v[182:185], v[214:217], v[64:67]
	s_setprio 0
	s_add_u32 s42, s40, 0x8000
	s_addc_u32 s43, s41, 0
	s_add_i32 s64, s64, s20
	v_lshl_add_u64 v[172:173], s[42:43], 0, v[156:157]
	s_mov_b32 m0, s64
	ds_read_b128 v[186:189], v177 offset:49152
	ds_read_b128 v[190:193], v177 offset:50176
	ds_read_b128 v[194:197], v177 offset:51200
	ds_read_b128 v[198:201], v177 offset:52224
	ds_read_b128 v[202:205], v177 offset:53248
	ds_read_b128 v[206:209], v177 offset:54272
	ds_read_b128 v[210:213], v177 offset:55296
	ds_read_b128 v[214:217], v177 offset:56320
	global_load_lds_dwordx4 v[172:173], off
	s_add_i32 m0, s64, 0x2000
	s_add_u32 s40, s40, 0xc000
	v_lshl_add_u64 v[172:173], s[42:43], 0, v[152:153]
	s_addc_u32 s41, s41, 0
	s_add_i32 s42, s65, s20
	global_load_lds_dwordx4 v[172:173], off
	v_lshl_add_u64 v[172:173], s[40:41], 0, v[156:157]
	s_mov_b32 m0, s42
	s_nop 0
	global_load_lds_dwordx4 v[172:173], off
	v_lshl_add_u64 v[172:173], s[40:41], 0, v[152:153]
	s_add_i32 m0, s42, 0x2000
	s_nop 0
	global_load_lds_dwordx4 v[172:173], off
	v_lshl_add_u64 v[172:173], s[38:39], 0, v[158:159]
	s_mov_b32 m0, s29
	s_nop 0
	global_load_lds_dwordx4 v[172:173], off
	v_lshl_add_u64 v[172:173], s[38:39], 0, v[154:155]
	s_mov_b32 m0, s30
	s_nop 0
	global_load_lds_dwordx4 v[172:173], off
	s_waitcnt vmcnt(8)
	s_waitcnt lgkmcnt(0)
	s_barrier
	s_setprio 1
	s_waitcnt lgkmcnt(0)
	v_mfma_f32_16x16x32_bf16 v[60:63], v[128:131], v[186:189], v[60:63]
	v_mfma_f32_16x16x32_bf16 v[60:63], v[132:135], v[190:193], v[60:63]
	v_mfma_f32_16x16x32_bf16 v[56:59], v[136:139], v[186:189], v[56:59]
	v_mfma_f32_16x16x32_bf16 v[56:59], v[140:143], v[190:193], v[56:59]
	v_mfma_f32_16x16x32_bf16 v[44:47], v[128:131], v[194:197], v[44:47]
	v_mfma_f32_16x16x32_bf16 v[44:47], v[132:135], v[198:201], v[44:47]
	v_mfma_f32_16x16x32_bf16 v[40:43], v[136:139], v[194:197], v[40:43]
	v_mfma_f32_16x16x32_bf16 v[40:43], v[140:143], v[198:201], v[40:43]
	v_mfma_f32_16x16x32_bf16 v[28:31], v[128:131], v[202:205], v[28:31]
	v_mfma_f32_16x16x32_bf16 v[28:31], v[132:135], v[206:209], v[28:31]
	v_mfma_f32_16x16x32_bf16 v[24:27], v[136:139], v[202:205], v[24:27]
	v_mfma_f32_16x16x32_bf16 v[24:27], v[140:143], v[206:209], v[24:27]
	v_mfma_f32_16x16x32_bf16 v[12:15], v[128:131], v[210:213], v[12:15]
	v_mfma_f32_16x16x32_bf16 v[12:15], v[132:135], v[214:217], v[12:15]
	v_mfma_f32_16x16x32_bf16 v[8:11], v[136:139], v[210:213], v[8:11]
	v_mfma_f32_16x16x32_bf16 v[8:11], v[140:143], v[214:217], v[8:11]
	s_setprio 0
	s_setprio 1
	v_mfma_f32_16x16x32_bf16 v[52:55], v[144:147], v[186:189], v[52:55]
	v_mfma_f32_16x16x32_bf16 v[52:55], v[148:151], v[190:193], v[52:55]
	v_mfma_f32_16x16x32_bf16 v[48:51], v[178:181], v[186:189], v[48:51]
	v_mfma_f32_16x16x32_bf16 v[48:51], v[182:185], v[190:193], v[48:51]
	v_mfma_f32_16x16x32_bf16 v[36:39], v[144:147], v[194:197], v[36:39]
	v_mfma_f32_16x16x32_bf16 v[36:39], v[148:151], v[198:201], v[36:39]
	v_mfma_f32_16x16x32_bf16 v[32:35], v[178:181], v[194:197], v[32:35]
	v_mfma_f32_16x16x32_bf16 v[32:35], v[182:185], v[198:201], v[32:35]
	v_mfma_f32_16x16x32_bf16 v[20:23], v[144:147], v[202:205], v[20:23]
	v_mfma_f32_16x16x32_bf16 v[20:23], v[148:151], v[206:209], v[20:23]
	v_mfma_f32_16x16x32_bf16 v[16:19], v[178:181], v[202:205], v[16:19]
	v_mfma_f32_16x16x32_bf16 v[16:19], v[182:185], v[206:209], v[16:19]
	s_setprio 2
	s_barrier
	v_mfma_f32_16x16x32_bf16 v[4:7], v[144:147], v[210:213], v[4:7]
	v_mfma_f32_16x16x32_bf16 v[4:7], v[148:151], v[214:217], v[4:7]
	v_mfma_f32_16x16x32_bf16 v[0:3], v[178:181], v[210:213], v[0:3]
	v_mfma_f32_16x16x32_bf16 v[0:3], v[182:185], v[214:217], v[0:3]
	s_setprio 0
	s_add_u32 s36, s36, 0x10000
	s_addc_u32 s37, s37, 0
	s_add_u32 s78, s78, 0x10000
	s_addc_u32 s82, s82, 0
	s_cmp_ge_u32 s84, s26
	s_mov_b32 s38, s84
	s_cbranch_scc0 .LBB0_193
	s_and_b64 vcc, exec, s[60:61]
	s_cbranch_vccz .LBB0_196
	s_barrier

; #define PG8_STAGE(bufoff, gbase, voff) do { _Pragma("unroll") for (int _i = 0; _i < 2; ++_i) \
;         __builtin_amdgcn_global_load_lds((const unsigned*)((const char*)(gbase) + (voff)[_i]), (PG8_LAS unsigned*)(lds + (bufoff) + ldsw + _i * 8192), 16, 0, 0); } while (0)
; #define PG8_LDA(dst, b, h) do { _Pragma("unroll") for (int m = 0; m < 4; ++m) _Pragma("unroll") for (int k = 0; k < 2; ++k) dst[m][k] = *(const PG8_LAS bf16x8*)(lds + PG8_SA(b, h) + aoff + m * 2048 + k * 1024); } while (0)
; #define PG8_LDB(dst, b, h) do { _Pragma("unroll") for (int n = 0; n < 2; ++n) _Pragma("unroll") for (int k = 0; k < 2; ++k) dst[n][k] = *(const PG8_LAS bf16x8*)(lds + PG8_SB(b, h) + boff + n * 2048 + k * 1024); } while (0)
; #define PG8_WAIT_V(n) asm volatile("s_waitcnt vmcnt(" #n ")" ::: "memory")
; #define PG8_WAIT_L(n) asm volatile("s_waitcnt lgkmcnt(" #n ")" ::: "memory")
; #define PG8_BAR __builtin_amdgcn_s_barrier()
; #define PG8_SCHED __builtin_amdgcn_sched_barrier(0)
; template <class Epi, class Sched, bool ALIGN_EPI = false, bool SP2 = false>
; __device__ __forceinline__ void gemm_phase(PG8_LAS unsigned char* lds, const Gemm g, const Sched& S, const Epi& E) {
;     ...
;         const char* nA = has_next ? (const char*)g.A + (size_t)nxt.pm * tstep : cA; const char* nB = has_next ? (const char*)g.Bt + (size_t)nxt.pn * tstep : cB;
;         for (int t = 0; t < nt; t += 2) {
;             const bool last = (t == nt - 2);
;             const char* a1 = cA + (size_t)(t + 1) * kstepB;
;             const char* a2 = last ? nA : cA + (size_t)(t + 2) * kstepB; const char* b2 = last ? nB : cB + (size_t)(t + 2) * kstepB;
;             const char* a3 = a2 + kstepB; const char* b3 = b2 + kstepB;
;             if (last && has_next) S.a_ready(nxt);
;             if constexpr (SP2) {
;             PG8_LDB(B0, 0, 0); PG8_LDB(B1, 0, 1); PG8_SCHED; PG8_LDA(At, 0, 0); PG8_STAGE(PG8_SA(1, 1), a1 + hstepB, voffA);
;             PG8_WAIT_V(8); PG8_WAIT_L(0); PG8_BAR; PG8_MMA(0, 0, At, B0); PG8_MMA(0, 1, At, B1); PG8_BAR; PG8_SCHED;
;             PG8_LDA(At, 0, 1); PG8_STAGE(PG8_SB(0, 0), b2, voffB); PG8_STAGE(PG8_SB(0, 1), b2 + hstepB, voffB); PG8_STAGE(PG8_SA(0, 0), a2, voffA);
;             PG8_WAIT_V(8); PG8_WAIT_L(0); PG8_BAR; PG8_MMA(1, 0, At, B0); PG8_MMA(1, 1, At, B1); PG8_BAR; PG8_SCHED;
.LBB0_232:
	s_add_u32 s31, s36, 0x4000
	s_addc_u32 s38, s37, 0
	s_cmp_eq_u32 s30, 28
	s_cselect_b32 s42, s26, s31
	s_cselect_b32 s43, s13, s38
	s_cselect_b32 s40, s27, s28
	s_cselect_b32 s41, s11, s29
	s_add_u32 s38, s42, 0x8000
	s_addc_u32 s39, s43, 0
	s_add_i32 s31, 0, 0x10000
	s_add_i32 s60, 0, 0x14000
	v_add_u32_e32 v152, s31, v169
	v_add_u32_e32 v175, s60, v169
	ds_read_b128 v[128:131], v152
	ds_read_b128 v[132:135], v152 offset:1024
	ds_read_b128 v[148:151], v152 offset:2048
	ds_read_b128 v[152:155], v152 offset:3072
	ds_read_b128 v[156:159], v175
	ds_read_b128 v[160:163], v175 offset:1024
	ds_read_b128 v[164:167], v175 offset:2048
	ds_read_b128 v[176:179], v175 offset:3072
	v_lshl_add_u64 v[212:213], s[36:37], 0, v[144:145]
	s_add_i32 m0, s17, 0xc000
	ds_read_b128 v[180:183], v174
	ds_read_b128 v[184:187], v174 offset:1024
	ds_read_b128 v[188:191], v174 offset:2048
	ds_read_b128 v[192:195], v174 offset:3072
	ds_read_b128 v[196:199], v174 offset:4096
	ds_read_b128 v[200:203], v174 offset:5120
	ds_read_b128 v[204:207], v174 offset:6144
	ds_read_b128 v[208:211], v174 offset:7168
	global_load_lds_dwordx4 v[212:213], off
	v_lshl_add_u64 v[212:213], s[36:37], 0, v[146:147]
	s_add_i32 m0, s17, 0xe000
	s_nop 0
	global_load_lds_dwordx4 v[212:213], off
	s_waitcnt vmcnt(8)
	s_waitcnt lgkmcnt(0)
	s_barrier
	s_setprio 1
	s_waitcnt lgkmcnt(0)
	v_mfma_f32_16x16x32_bf16 v[124:127], v[128:131], v[180:183], v[124:127]
	v_mfma_f32_16x16x32_bf16 v[124:127], v[132:135], v[184:187], v[124:127]
	v_mfma_f32_16x16x32_bf16 v[120:123], v[148:151], v[180:183], v[120:123]
	v_mfma_f32_16x16x32_bf16 v[120:123], v[152:155], v[184:187], v[120:123]
	v_mfma_f32_16x16x32_bf16 v[108:111], v[128:131], v[188:191], v[108:111]
	v_mfma_f32_16x16x32_bf16 v[108:111], v[132:135], v[192:195], v[108:111]
	v_mfma_f32_16x16x32_bf16 v[104:107], v[148:151], v[188:191], v[104:107]
	v_mfma_f32_16x16x32_bf16 v[104:107], v[152:155], v[192:195], v[104:107]
	v_mfma_f32_16x16x32_bf16 v[92:95], v[128:131], v[196:199], v[92:95]
	v_mfma_f32_16x16x32_bf16 v[92:95], v[132:135], v[200:203], v[92:95]
	v_mfma_f32_16x16x32_bf16 v[88:91], v[148:151], v[196:199], v[88:91]
	v_mfma_f32_16x16x32_bf16 v[88:91], v[152:155], v[200:203], v[88:91]
	v_mfma_f32_16x16x32_bf16 v[76:79], v[128:131], v[204:207], v[76:79]
	v_mfma_f32_16x16x32_bf16 v[76:79], v[132:135], v[208:211], v[76:79]
	v_mfma_f32_16x16x32_bf16 v[72:75], v[148:151], v[204:207], v[72:75]
	v_mfma_f32_16x16x32_bf16 v[72:75], v[152:155], v[208:211], v[72:75]
	s_setprio 0
	s_setprio 1
	v_mfma_f32_16x16x32_bf16 v[116:119], v[156:159], v[180:183], v[116:119]
	v_mfma_f32_16x16x32_bf16 v[116:119], v[160:163], v[184:187], v[116:119]
	v_mfma_f32_16x16x32_bf16 v[112:115], v[164:167], v[180:183], v[112:115]
	v_mfma_f32_16x16x32_bf16 v[112:115], v[176:179], v[184:187], v[112:115]
	v_mfma_f32_16x16x32_bf16 v[100:103], v[156:159], v[188:191], v[100:103]
	v_mfma_f32_16x16x32_bf16 v[100:103], v[160:163], v[192:195], v[100:103]
	v_mfma_f32_16x16x32_bf16 v[96:99], v[164:167], v[188:191], v[96:99]
	v_mfma_f32_16x16x32_bf16 v[96:99], v[176:179], v[192:195], v[96:99]
	v_mfma_f32_16x16x32_bf16 v[84:87], v[156:159], v[196:199], v[84:87]
	v_mfma_f32_16x16x32_bf16 v[84:87], v[160:163], v[200:203], v[84:87]
	v_mfma_f32_16x16x32_bf16 v[80:83], v[164:167], v[196:199], v[80:83]
	v_mfma_f32_16x16x32_bf16 v[80:83], v[176:179], v[200:203], v[80:83]
	s_setprio 2
	s_barrier
	v_mfma_f32_16x16x32_bf16 v[68:71], v[156:159], v[204:207], v[68:71]
	v_mfma_f32_16x16x32_bf16 v[68:71], v[160:163], v[208:211], v[68:71]
	v_mfma_f32_16x16x32_bf16 v[64:67], v[164:167], v[204:207], v[64:67]
	v_mfma_f32_16x16x32_bf16 v[64:67], v[176:179], v[208:211], v[64:67]
	s_setprio 0
	s_add_i32 s31, s31, s14
	v_lshl_add_u64 v[212:213], s[40:41], 0, v[220:221]
	s_mov_b32 m0, s31
	ds_read_b128 v[180:183], v174 offset:16384
	ds_read_b128 v[184:187], v174 offset:17408
	ds_read_b128 v[188:191], v174 offset:18432
	ds_read_b128 v[192:195], v174 offset:19456
	ds_read_b128 v[196:199], v174 offset:20480
	ds_read_b128 v[200:203], v174 offset:21504
	ds_read_b128 v[204:207], v174 offset:22528
	ds_read_b128 v[208:211], v174 offset:23552
	global_load_lds_dwordx4 v[212:213], off
	s_add_i32 m0, s31, 0x2000
	s_add_u32 s44, s40, 0x4000
	v_lshl_add_u64 v[212:213], s[40:41], 0, v[136:137]
	s_addc_u32 s45, s41, 0
	s_add_i32 s31, s60, s14
	global_load_lds_dwordx4 v[212:213], off
	v_lshl_add_u64 v[212:213], s[44:45], 0, v[220:221]
	s_mov_b32 m0, s31
	s_nop 0
	global_load_lds_dwordx4 v[212:213], off
	v_lshl_add_u64 v[212:213], s[44:45], 0, v[136:137]
	s_add_i32 m0, s31, 0x2000
	s_nop 0
	global_load_lds_dwordx4 v[212:213], off
	v_lshl_add_u64 v[212:213], s[42:43], 0, v[140:141]
	s_mov_b32 m0, s17
	s_nop 0
	global_load_lds_dwordx4 v[212:213], off
	v_lshl_add_u64 v[212:213], s[42:43], 0, v[138:139]
	s_mov_b32 m0, s18
	s_nop 0
	global_load_lds_dwordx4 v[212:213], off
	s_waitcnt vmcnt(8)
	s_waitcnt lgkmcnt(0)
	s_barrier
; #define PG8_STAGE(bufoff, gbase, voff) do { _Pragma("unroll") for (int _i = 0; _i < 2; ++_i) \
;         __builtin_amdgcn_global_load_lds((const unsigned*)((const char*)(gbase) + (voff)[_i]), (PG8_LAS unsigned*)(lds + (bufoff) + ldsw + _i * 8192), 16, 0, 0); } while (0)
; #define PG8_LDA(dst, b, h) do { _Pragma("unroll") for (int m = 0; m < 4; ++m) _Pragma("unroll") for (int k = 0; k < 2; ++k) dst[m][k] = *(const PG8_LAS bf16x8*)(lds + PG8_SA(b, h) + aoff + m * 2048 + k * 1024); } while (0)
; #define PG8_LDB(dst, b, h) do { _Pragma("unroll") for (int n = 0; n < 2; ++n) _Pragma("unroll") for (int k = 0; k < 2; ++k) dst[n][k] = *(const PG8_LAS bf16x8*)(lds + PG8_SB(b, h) + boff + n * 2048 + k * 1024); } while (0)
; #define PG8_MMA(ai, bj, At, Bt) do { __builtin_amdgcn_s_setprio(1); _Pragma("unroll") for (int m = 0; m < 4; ++m) _Pragma("unroll") for (int n = 0; n < 2; ++n) _Pragma("unroll") for (int k = 0; k < 2; ++k) \
;         acc[ai][bj][m][n] = __builtin_amdgcn_mfma_f32_16x16x32_bf16(Bt[n][k], At[m][k], acc[ai][bj][m][n], 0, 0, 0); __builtin_amdgcn_s_setprio(0); } while (0)
; #define PG8_WAIT_V(n) asm volatile("s_waitcnt vmcnt(" #n ")" ::: "memory")
; #define PG8_WAIT_L(n) asm volatile("s_waitcnt lgkmcnt(" #n ")" ::: "memory")
; #define PG8_BAR __builtin_amdgcn_s_barrier()
; #define PG8_SCHED __builtin_amdgcn_sched_barrier(0)
; template <class Epi, class Sched, bool ALIGN_EPI = false, bool SP2 = false>
; __device__ __forceinline__ void gemm_phase(PG8_LAS unsigned char* lds, const Gemm g, const Sched& S, const Epi& E) {
;     ...
;             PG8_WAIT_V(8); PG8_WAIT_L(0); PG8_BAR; PG8_MMA(1, 0, At, B0); PG8_MMA(1, 1, At, B1); PG8_BAR; PG8_SCHED;
;             PG8_LDB(B0, 1, 0); PG8_LDB(B1, 1, 1); PG8_SCHED; PG8_LDA(At, 1, 0); PG8_STAGE(PG8_SA(0, 1), a2 + hstepB, voffA);
;             PG8_WAIT_V(8); PG8_WAIT_L(0); PG8_BAR; PG8_MMA(0, 0, At, B0); PG8_MMA(0, 1, At, B1); PG8_BAR; PG8_SCHED;
;             PG8_LDA(At, 1, 1); PG8_STAGE(PG8_SB(1, 0), b3, voffB); PG8_STAGE(PG8_SB(1, 1), b3 + hstepB, voffB); PG8_STAGE(PG8_SA(1, 0), a3, voffA);
	s_setprio 1
	s_waitcnt lgkmcnt(0)
	v_mfma_f32_16x16x32_bf16 v[60:63], v[128:131], v[180:183], v[60:63]
	v_mfma_f32_16x16x32_bf16 v[60:63], v[132:135], v[184:187], v[60:63]
	v_mfma_f32_16x16x32_bf16 v[56:59], v[148:151], v[180:183], v[56:59]
	v_mfma_f32_16x16x32_bf16 v[56:59], v[152:155], v[184:187], v[56:59]
	v_mfma_f32_16x16x32_bf16 v[48:51], v[128:131], v[188:191], v[48:51]
	v_mfma_f32_16x16x32_bf16 v[48:51], v[132:135], v[192:195], v[48:51]
	v_mfma_f32_16x16x32_bf16 v[40:43], v[148:151], v[188:191], v[40:43]
	v_mfma_f32_16x16x32_bf16 v[40:43], v[152:155], v[192:195], v[40:43]
	v_mfma_f32_16x16x32_bf16 v[32:35], v[128:131], v[196:199], v[32:35]
	v_mfma_f32_16x16x32_bf16 v[32:35], v[132:135], v[200:203], v[32:35]
	v_mfma_f32_16x16x32_bf16 v[24:27], v[148:151], v[196:199], v[24:27]
	v_mfma_f32_16x16x32_bf16 v[24:27], v[152:155], v[200:203], v[24:27]
	v_mfma_f32_16x16x32_bf16 v[16:19], v[128:131], v[204:207], v[16:19]
	v_mfma_f32_16x16x32_bf16 v[16:19], v[132:135], v[208:211], v[16:19]
	v_mfma_f32_16x16x32_bf16 v[8:11], v[148:151], v[204:207], v[8:11]
	v_mfma_f32_16x16x32_bf16 v[8:11], v[152:155], v[208:211], v[8:11]
	s_setprio 0
	s_setprio 1
	v_mfma_f32_16x16x32_bf16 v[52:55], v[156:159], v[180:183], v[52:55]
	v_mfma_f32_16x16x32_bf16 v[52:55], v[160:163], v[184:187], v[52:55]
	v_mfma_f32_16x16x32_bf16 v[44:47], v[164:167], v[180:183], v[44:47]
	v_mfma_f32_16x16x32_bf16 v[44:47], v[176:179], v[184:187], v[44:47]
	v_mfma_f32_16x16x32_bf16 v[36:39], v[156:159], v[188:191], v[36:39]
	v_mfma_f32_16x16x32_bf16 v[36:39], v[160:163], v[192:195], v[36:39]
	v_mfma_f32_16x16x32_bf16 v[28:31], v[164:167], v[188:191], v[28:31]
	v_mfma_f32_16x16x32_bf16 v[28:31], v[176:179], v[192:195], v[28:31]
	v_mfma_f32_16x16x32_bf16 v[20:23], v[156:159], v[196:199], v[20:23]
	v_mfma_f32_16x16x32_bf16 v[20:23], v[160:163], v[200:203], v[20:23]
	v_mfma_f32_16x16x32_bf16 v[12:15], v[164:167], v[196:199], v[12:15]
	v_mfma_f32_16x16x32_bf16 v[12:15], v[176:179], v[200:203], v[12:15]
	s_setprio 2
	s_barrier
	v_mfma_f32_16x16x32_bf16 v[4:7], v[156:159], v[204:207], v[4:7]
	v_mfma_f32_16x16x32_bf16 v[4:7], v[160:163], v[208:211], v[4:7]
	v_mfma_f32_16x16x32_bf16 v[0:3], v[164:167], v[204:207], v[0:3]
	v_mfma_f32_16x16x32_bf16 v[0:3], v[176:179], v[208:211], v[0:3]
	s_setprio 0
	s_add_i32 s31, 0, 0x18000
	s_add_i32 s44, 0, 0x1c000
	v_add_u32_e32 v152, s31, v169
	v_add_u32_e32 v175, s44, v169
	ds_read_b128 v[128:131], v152
	ds_read_b128 v[132:135], v152 offset:1024
	ds_read_b128 v[148:151], v152 offset:2048
	ds_read_b128 v[152:155], v152 offset:3072
	ds_read_b128 v[156:159], v175
	ds_read_b128 v[160:163], v175 offset:1024
	ds_read_b128 v[164:167], v175 offset:2048
	ds_read_b128 v[176:179], v175 offset:3072
	s_add_u32 s42, s42, 0x4000
	s_addc_u32 s43, s43, 0
	s_mov_b32 m0, s19
	v_lshl_add_u64 v[212:213], s[42:43], 0, v[140:141]
	ds_read_b128 v[180:183], v174 offset:32768
	ds_read_b128 v[184:187], v174 offset:33792
	ds_read_b128 v[188:191], v174 offset:34816
	ds_read_b128 v[192:195], v174 offset:35840
	ds_read_b128 v[196:199], v174 offset:36864
	ds_read_b128 v[200:203], v174 offset:37888
	ds_read_b128 v[204:207], v174 offset:38912
	ds_read_b128 v[208:211], v174 offset:39936
	global_load_lds_dwordx4 v[212:213], off
	v_lshl_add_u64 v[212:213], s[42:43], 0, v[138:139]
	s_mov_b32 m0, s20
	s_nop 0
	global_load_lds_dwordx4 v[212:213], off
	s_waitcnt vmcnt(8)
	s_waitcnt lgkmcnt(0)
	s_barrier
	s_setprio 1
	s_waitcnt lgkmcnt(0)
	v_mfma_f32_16x16x32_bf16 v[124:127], v[128:131], v[180:183], v[124:127]
	v_mfma_f32_16x16x32_bf16 v[124:127], v[132:135], v[184:187], v[124:127]
	v_mfma_f32_16x16x32_bf16 v[120:123], v[148:151], v[180:183], v[120:123]
	v_mfma_f32_16x16x32_bf16 v[120:123], v[152:155], v[184:187], v[120:123]
	v_mfma_f32_16x16x32_bf16 v[108:111], v[128:131], v[188:191], v[108:111]
	v_mfma_f32_16x16x32_bf16 v[108:111], v[132:135], v[192:195], v[108:111]
	v_mfma_f32_16x16x32_bf16 v[104:107], v[148:151], v[188:191], v[104:107]
	v_mfma_f32_16x16x32_bf16 v[104:107], v[152:155], v[192:195], v[104:107]
	v_mfma_f32_16x16x32_bf16 v[92:95], v[128:131], v[196:199], v[92:95]
	v_mfma_f32_16x16x32_bf16 v[92:95], v[132:135], v[200:203], v[92:95]
	v_mfma_f32_16x16x32_bf16 v[88:91], v[148:151], v[196:199], v[88:91]
	v_mfma_f32_16x16x32_bf16 v[88:91], v[152:155], v[200:203], v[88:91]
	v_mfma_f32_16x16x32_bf16 v[76:79], v[128:131], v[204:207], v[76:79]
	v_mfma_f32_16x16x32_bf16 v[76:79], v[132:135], v[208:211], v[76:79]
	v_mfma_f32_16x16x32_bf16 v[72:75], v[148:151], v[204:207], v[72:75]
	v_mfma_f32_16x16x32_bf16 v[72:75], v[152:155], v[208:211], v[72:75]
	s_setprio 0
	s_setprio 1
	v_mfma_f32_16x16x32_bf16 v[116:119], v[156:159], v[180:183], v[116:119]
	v_mfma_f32_16x16x32_bf16 v[116:119], v[160:163], v[184:187], v[116:119]
	v_mfma_f32_16x16x32_bf16 v[112:115], v[164:167], v[180:183], v[112:115]
	v_mfma_f32_16x16x32_bf16 v[112:115], v[176:179], v[184:187], v[112:115]
	v_mfma_f32_16x16x32_bf16 v[100:103], v[156:159], v[188:191], v[100:103]
	v_mfma_f32_16x16x32_bf16 v[100:103], v[160:163], v[192:195], v[100:103]
	v_mfma_f32_16x16x32_bf16 v[96:99], v[164:167], v[188:191], v[96:99]
	v_mfma_f32_16x16x32_bf16 v[96:99], v[176:179], v[192:195], v[96:99]
	v_mfma_f32_16x16x32_bf16 v[84:87], v[156:159], v[196:199], v[84:87]
	v_mfma_f32_16x16x32_bf16 v[84:87], v[160:163], v[200:203], v[84:87]
	v_mfma_f32_16x16x32_bf16 v[80:83], v[164:167], v[196:199], v[80:83]
	v_mfma_f32_16x16x32_bf16 v[80:83], v[176:179], v[200:203], v[80:83]
	s_setprio 2
	s_barrier
; #define PG8_STAGE(bufoff, gbase, voff) do { _Pragma("unroll") for (int _i = 0; _i < 2; ++_i) \
;         __builtin_amdgcn_global_load_lds((const unsigned*)((const char*)(gbase) + (voff)[_i]), (PG8_LAS unsigned*)(lds + (bufoff) + ldsw + _i * 8192), 16, 0, 0); } while (0)
; #define PG8_LDA(dst, b, h) do { _Pragma("unroll") for (int m = 0; m < 4; ++m) _Pragma("unroll") for (int k = 0; k < 2; ++k) dst[m][k] = *(const PG8_LAS bf16x8*)(lds + PG8_SA(b, h) + aoff + m * 2048 + k * 1024); } while (0)
; #define PG8_MMA(ai, bj, At, Bt) do { __builtin_amdgcn_s_setprio(1); _Pragma("unroll") for (int m = 0; m < 4; ++m) _Pragma("unroll") for (int n = 0; n < 2; ++n) _Pragma("unroll") for (int k = 0; k < 2; ++k) \
;         acc[ai][bj][m][n] = __builtin_amdgcn_mfma_f32_16x16x32_bf16(Bt[n][k], At[m][k], acc[ai][bj][m][n], 0, 0, 0); __builtin_amdgcn_s_setprio(0); } while (0)
; #define PG8_WAIT_V(n) asm volatile("s_waitcnt vmcnt(" #n ")" ::: "memory")
; #define PG8_WAIT_L(n) asm volatile("s_waitcnt lgkmcnt(" #n ")" ::: "memory")
; #define PG8_BAR __builtin_amdgcn_s_barrier()
; #define PG8_SCHED __builtin_amdgcn_sched_barrier(0)
; template <class Epi, class Sched, bool ALIGN_EPI = false, bool SP2 = false>
; __device__ __forceinline__ void gemm_phase(PG8_LAS unsigned char* lds, const Gemm g, const Sched& S, const Epi& E) {
;     ...
;             PG8_LDA(At, 1, 1); PG8_STAGE(PG8_SB(1, 0), b3, voffB); PG8_STAGE(PG8_SB(1, 1), b3 + hstepB, voffB); PG8_STAGE(PG8_SA(1, 0), a3, voffA);
;             PG8_WAIT_V(8); PG8_WAIT_L(0); PG8_BAR; PG8_MMA(1, 0, At, B0); PG8_MMA(1, 1, At, B1); PG8_BAR; PG8_SCHED;
	v_mfma_f32_16x16x32_bf16 v[68:71], v[156:159], v[204:207], v[68:71]
	v_mfma_f32_16x16x32_bf16 v[68:71], v[160:163], v[208:211], v[68:71]
	v_mfma_f32_16x16x32_bf16 v[64:67], v[164:167], v[204:207], v[64:67]
	v_mfma_f32_16x16x32_bf16 v[64:67], v[176:179], v[208:211], v[64:67]
	s_setprio 0
	s_add_u32 s42, s40, 0x8000
	s_addc_u32 s43, s41, 0
	s_add_i32 s31, s31, s14
	v_lshl_add_u64 v[212:213], s[42:43], 0, v[220:221]
	s_mov_b32 m0, s31
	ds_read_b128 v[180:183], v174 offset:49152
	ds_read_b128 v[184:187], v174 offset:50176
	ds_read_b128 v[188:191], v174 offset:51200
	ds_read_b128 v[192:195], v174 offset:52224
	ds_read_b128 v[196:199], v174 offset:53248
	ds_read_b128 v[200:203], v174 offset:54272
	ds_read_b128 v[204:207], v174 offset:55296
	ds_read_b128 v[208:211], v174 offset:56320
	global_load_lds_dwordx4 v[212:213], off
	s_add_i32 m0, s31, 0x2000
	s_add_u32 s40, s40, 0xc000
	v_lshl_add_u64 v[212:213], s[42:43], 0, v[136:137]
	s_addc_u32 s41, s41, 0
	s_add_i32 s31, s44, s14
	global_load_lds_dwordx4 v[212:213], off
	v_lshl_add_u64 v[212:213], s[40:41], 0, v[220:221]
	s_mov_b32 m0, s31
	s_nop 0
	global_load_lds_dwordx4 v[212:213], off
	v_lshl_add_u64 v[212:213], s[40:41], 0, v[136:137]
	s_add_i32 m0, s31, 0x2000
	s_nop 0
	global_load_lds_dwordx4 v[212:213], off
	v_lshl_add_u64 v[212:213], s[38:39], 0, v[140:141]
	s_mov_b32 m0, s21
	s_nop 0
	global_load_lds_dwordx4 v[212:213], off
	v_lshl_add_u64 v[212:213], s[38:39], 0, v[138:139]
	s_mov_b32 m0, s22
	s_nop 0
	global_load_lds_dwordx4 v[212:213], off
	s_waitcnt vmcnt(8)
	s_waitcnt lgkmcnt(0)
	s_barrier
	s_setprio 1
	s_waitcnt lgkmcnt(0)
	v_mfma_f32_16x16x32_bf16 v[60:63], v[128:131], v[180:183], v[60:63]
	v_mfma_f32_16x16x32_bf16 v[60:63], v[132:135], v[184:187], v[60:63]
	v_mfma_f32_16x16x32_bf16 v[56:59], v[148:151], v[180:183], v[56:59]
	v_mfma_f32_16x16x32_bf16 v[56:59], v[152:155], v[184:187], v[56:59]
	v_mfma_f32_16x16x32_bf16 v[48:51], v[128:131], v[188:191], v[48:51]
	v_mfma_f32_16x16x32_bf16 v[48:51], v[132:135], v[192:195], v[48:51]
	v_mfma_f32_16x16x32_bf16 v[40:43], v[148:151], v[188:191], v[40:43]
	v_mfma_f32_16x16x32_bf16 v[40:43], v[152:155], v[192:195], v[40:43]
	v_mfma_f32_16x16x32_bf16 v[32:35], v[128:131], v[196:199], v[32:35]
	v_mfma_f32_16x16x32_bf16 v[32:35], v[132:135], v[200:203], v[32:35]
	v_mfma_f32_16x16x32_bf16 v[24:27], v[148:151], v[196:199], v[24:27]
	v_mfma_f32_16x16x32_bf16 v[24:27], v[152:155], v[200:203], v[24:27]
	v_mfma_f32_16x16x32_bf16 v[16:19], v[128:131], v[204:207], v[16:19]
	v_mfma_f32_16x16x32_bf16 v[16:19], v[132:135], v[208:211], v[16:19]
	v_mfma_f32_16x16x32_bf16 v[8:11], v[148:151], v[204:207], v[8:11]
	v_mfma_f32_16x16x32_bf16 v[8:11], v[152:155], v[208:211], v[8:11]
	s_setprio 0
	s_setprio 1
	v_mfma_f32_16x16x32_bf16 v[52:55], v[156:159], v[180:183], v[52:55]
	v_mfma_f32_16x16x32_bf16 v[52:55], v[160:163], v[184:187], v[52:55]
	v_mfma_f32_16x16x32_bf16 v[44:47], v[164:167], v[180:183], v[44:47]
	v_mfma_f32_16x16x32_bf16 v[44:47], v[176:179], v[184:187], v[44:47]
	v_mfma_f32_16x16x32_bf16 v[36:39], v[156:159], v[188:191], v[36:39]
	v_mfma_f32_16x16x32_bf16 v[36:39], v[160:163], v[192:195], v[36:39]
	v_mfma_f32_16x16x32_bf16 v[28:31], v[164:167], v[188:191], v[28:31]
	v_mfma_f32_16x16x32_bf16 v[28:31], v[176:179], v[192:195], v[28:31]
	v_mfma_f32_16x16x32_bf16 v[20:23], v[156:159], v[196:199], v[20:23]
	v_mfma_f32_16x16x32_bf16 v[20:23], v[160:163], v[200:203], v[20:23]
	v_mfma_f32_16x16x32_bf16 v[12:15], v[164:167], v[196:199], v[12:15]
	v_mfma_f32_16x16x32_bf16 v[12:15], v[176:179], v[200:203], v[12:15]
	s_setprio 2
	s_barrier
	v_mfma_f32_16x16x32_bf16 v[4:7], v[156:159], v[204:207], v[4:7]
	v_mfma_f32_16x16x32_bf16 v[4:7], v[160:163], v[208:211], v[4:7]
	v_mfma_f32_16x16x32_bf16 v[0:3], v[164:167], v[204:207], v[0:3]
	v_mfma_f32_16x16x32_bf16 v[0:3], v[176:179], v[208:211], v[0:3]
	s_setprio 0
	s_add_i32 s30, s30, 2
	s_add_u32 s36, s36, 0x10000
	s_addc_u32 s37, s37, 0
	s_add_u32 s28, s28, 0x10000
	s_addc_u32 s29, s29, 0
	s_cmp_gt_u32 s30, 29
	s_cbranch_scc0 .LBB0_232
	s_and_b64 vcc, exec, s[8:9]
	s_cbranch_vccz .LBB0_235
	s_barrier

; #define PG8_STAGE(bufoff, gbase, voff) do { _Pragma("unroll") for (int _i = 0; _i < 2; ++_i) \
;         __builtin_amdgcn_global_load_lds((const unsigned*)((const char*)(gbase) + (voff)[_i]), (PG8_LAS unsigned*)(lds + (bufoff) + ldsw + _i * 8192), 16, 0, 0); } while (0)
; #define PG8_LDA(dst, b, h) do { _Pragma("unroll") for (int m = 0; m < 4; ++m) _Pragma("unroll") for (int k = 0; k < 2; ++k) dst[m][k] = *(const PG8_LAS bf16x8*)(lds + PG8_SA(b, h) + aoff + m * 2048 + k * 1024); } while (0)
; #define PG8_LDB(dst, b, h) do { _Pragma("unroll") for (int n = 0; n < 2; ++n) _Pragma("unroll") for (int k = 0; k < 2; ++k) dst[n][k] = *(const PG8_LAS bf16x8*)(lds + PG8_SB(b, h) + boff + n * 2048 + k * 1024); } while (0)
; #define PG8_WAIT_V(n) asm volatile("s_waitcnt vmcnt(" #n ")" ::: "memory")
; #define PG8_WAIT_L(n) asm volatile("s_waitcnt lgkmcnt(" #n ")" ::: "memory")
; #define PG8_BAR __builtin_amdgcn_s_barrier()
; #define PG8_SCHED __builtin_amdgcn_sched_barrier(0)
; template <class Epi, class Sched, bool ALIGN_EPI = false, bool SP2 = false>
; __device__ __forceinline__ void gemm_phase(PG8_LAS unsigned char* lds, const Gemm g, const Sched& S, const Epi& E) {
;     ...
;         const char* nA = has_next ? (const char*)g.A + (size_t)nxt.pm * tstep : cA; const char* nB = has_next ? (const char*)g.Bt + (size_t)nxt.pn * tstep : cB;
;         for (int t = 0; t < nt; t += 2) {
;             const bool last = (t == nt - 2);
;             const char* a1 = cA + (size_t)(t + 1) * kstepB;
;             const char* a2 = last ? nA : cA + (size_t)(t + 2) * kstepB; const char* b2 = last ? nB : cB + (size_t)(t + 2) * kstepB;
;             const char* a3 = a2 + kstepB; const char* b3 = b2 + kstepB;
;             if (last && has_next) S.a_ready(nxt);
;             if constexpr (SP2) {
;             PG8_LDB(B0, 0, 0); PG8_LDB(B1, 0, 1); PG8_SCHED; PG8_LDA(At, 0, 0); PG8_STAGE(PG8_SA(1, 1), a1 + hstepB, voffA);
;             PG8_WAIT_V(8); PG8_WAIT_L(0); PG8_BAR; PG8_MMA(0, 0, At, B0); PG8_MMA(0, 1, At, B1); PG8_BAR; PG8_SCHED;
;             PG8_LDA(At, 0, 1); PG8_STAGE(PG8_SB(0, 0), b2, voffB); PG8_STAGE(PG8_SB(0, 1), b2 + hstepB, voffB); PG8_STAGE(PG8_SA(0, 0), a2, voffA);
;             PG8_WAIT_V(8); PG8_WAIT_L(0); PG8_BAR; PG8_MMA(1, 0, At, B0); PG8_MMA(1, 1, At, B1); PG8_BAR; PG8_SCHED;
.LBB0_263:
	s_add_u32 s38, s36, 0x4000
	s_addc_u32 s39, s37, 0
	s_cmp_eq_u32 s62, 28
	s_cselect_b32 s42, s30, s38
	s_cselect_b32 s43, s13, s39
	s_cselect_b32 s40, s31, s44
	s_cselect_b32 s41, s11, s45
	s_add_u32 s38, s42, 0x8000
	s_addc_u32 s39, s43, 0
	s_add_i32 s63, 0, 0x10000
	v_add_u32_e32 v151, s63, v165
	s_add_i32 s75, 0, 0x14000
	ds_read_b128 v[128:131], v151
	ds_read_b128 v[132:135], v151 offset:1024
	ds_read_b128 v[152:155], v151 offset:2048
	ds_read_b128 v[156:159], v151 offset:3072
	v_add_u32_e32 v151, s75, v165
	ds_read_b128 v[160:163], v151
	ds_read_b128 v[170:173], v151 offset:1024
	ds_read_b128 v[174:177], v151 offset:2048
	ds_read_b128 v[178:181], v151 offset:3072
	v_lshl_add_u64 v[214:215], s[36:37], 0, v[146:147]
	s_add_i32 m0, s19, 0xc000
	ds_read_b128 v[182:185], v168
	ds_read_b128 v[186:189], v168 offset:1024
	ds_read_b128 v[190:193], v168 offset:2048
	ds_read_b128 v[194:197], v168 offset:3072
	ds_read_b128 v[198:201], v168 offset:4096
	ds_read_b128 v[202:205], v168 offset:5120
	ds_read_b128 v[206:209], v168 offset:6144
	ds_read_b128 v[210:213], v168 offset:7168
	global_load_lds_dwordx4 v[214:215], off
	v_lshl_add_u64 v[214:215], s[36:37], 0, v[148:149]
	s_add_i32 m0, s19, 0xe000
	s_nop 0
	global_load_lds_dwordx4 v[214:215], off
	s_waitcnt vmcnt(8)
	s_waitcnt lgkmcnt(0)
	s_barrier
	s_setprio 1
	s_waitcnt lgkmcnt(0)
	v_mfma_f32_16x16x32_bf16 v[124:127], v[128:131], v[182:185], v[124:127]
	v_mfma_f32_16x16x32_bf16 v[124:127], v[132:135], v[186:189], v[124:127]
	v_mfma_f32_16x16x32_bf16 v[116:119], v[152:155], v[182:185], v[116:119]
	v_mfma_f32_16x16x32_bf16 v[116:119], v[156:159], v[186:189], v[116:119]
	v_mfma_f32_16x16x32_bf16 v[108:111], v[128:131], v[190:193], v[108:111]
	v_mfma_f32_16x16x32_bf16 v[108:111], v[132:135], v[194:197], v[108:111]
	v_mfma_f32_16x16x32_bf16 v[100:103], v[152:155], v[190:193], v[100:103]
	v_mfma_f32_16x16x32_bf16 v[100:103], v[156:159], v[194:197], v[100:103]
	v_mfma_f32_16x16x32_bf16 v[92:95], v[128:131], v[198:201], v[92:95]
	v_mfma_f32_16x16x32_bf16 v[92:95], v[132:135], v[202:205], v[92:95]
	v_mfma_f32_16x16x32_bf16 v[84:87], v[152:155], v[198:201], v[84:87]
	v_mfma_f32_16x16x32_bf16 v[84:87], v[156:159], v[202:205], v[84:87]
	v_mfma_f32_16x16x32_bf16 v[76:79], v[128:131], v[206:209], v[76:79]
	v_mfma_f32_16x16x32_bf16 v[76:79], v[132:135], v[210:213], v[76:79]
	v_mfma_f32_16x16x32_bf16 v[68:71], v[152:155], v[206:209], v[68:71]
	v_mfma_f32_16x16x32_bf16 v[68:71], v[156:159], v[210:213], v[68:71]
	s_setprio 0
	s_setprio 1
	v_mfma_f32_16x16x32_bf16 v[120:123], v[160:163], v[182:185], v[120:123]
	v_mfma_f32_16x16x32_bf16 v[120:123], v[170:173], v[186:189], v[120:123]
	v_mfma_f32_16x16x32_bf16 v[112:115], v[174:177], v[182:185], v[112:115]
	v_mfma_f32_16x16x32_bf16 v[112:115], v[178:181], v[186:189], v[112:115]
	v_mfma_f32_16x16x32_bf16 v[104:107], v[160:163], v[190:193], v[104:107]
	v_mfma_f32_16x16x32_bf16 v[104:107], v[170:173], v[194:197], v[104:107]
	v_mfma_f32_16x16x32_bf16 v[96:99], v[174:177], v[190:193], v[96:99]
	v_mfma_f32_16x16x32_bf16 v[96:99], v[178:181], v[194:197], v[96:99]
	v_mfma_f32_16x16x32_bf16 v[88:91], v[160:163], v[198:201], v[88:91]
	v_mfma_f32_16x16x32_bf16 v[88:91], v[170:173], v[202:205], v[88:91]
	v_mfma_f32_16x16x32_bf16 v[80:83], v[174:177], v[198:201], v[80:83]
	v_mfma_f32_16x16x32_bf16 v[80:83], v[178:181], v[202:205], v[80:83]
	s_setprio 2
	s_barrier
	v_mfma_f32_16x16x32_bf16 v[72:75], v[160:163], v[206:209], v[72:75]
	v_mfma_f32_16x16x32_bf16 v[72:75], v[170:173], v[210:213], v[72:75]
	v_mfma_f32_16x16x32_bf16 v[64:67], v[174:177], v[206:209], v[64:67]
	v_mfma_f32_16x16x32_bf16 v[64:67], v[178:181], v[210:213], v[64:67]
	s_setprio 0
	s_add_i32 s63, s63, s16
	v_lshl_add_u64 v[214:215], s[40:41], 0, v[140:141]
	s_mov_b32 m0, s63
	ds_read_b128 v[182:185], v168 offset:16384
	ds_read_b128 v[186:189], v168 offset:17408
	ds_read_b128 v[190:193], v168 offset:18432
	ds_read_b128 v[194:197], v168 offset:19456
	ds_read_b128 v[198:201], v168 offset:20480
	ds_read_b128 v[202:205], v168 offset:21504
	ds_read_b128 v[206:209], v168 offset:22528
	ds_read_b128 v[210:213], v168 offset:23552
	global_load_lds_dwordx4 v[214:215], off
	s_add_i32 m0, s63, 0x2000
	s_add_u32 s66, s40, 0x4000
	v_lshl_add_u64 v[214:215], s[40:41], 0, v[136:137]
	s_addc_u32 s67, s41, 0
	s_add_i32 s63, s75, s16
	global_load_lds_dwordx4 v[214:215], off
	v_lshl_add_u64 v[214:215], s[66:67], 0, v[140:141]
	s_mov_b32 m0, s63
	s_nop 0
	global_load_lds_dwordx4 v[214:215], off
	v_lshl_add_u64 v[214:215], s[66:67], 0, v[136:137]
	s_add_i32 m0, s63, 0x2000
	s_nop 0
	global_load_lds_dwordx4 v[214:215], off
	v_lshl_add_u64 v[214:215], s[42:43], 0, v[142:143]
	s_mov_b32 m0, s19
	s_nop 0
	global_load_lds_dwordx4 v[214:215], off
	v_lshl_add_u64 v[214:215], s[42:43], 0, v[138:139]
	s_mov_b32 m0, s20
	s_nop 0
	global_load_lds_dwordx4 v[214:215], off
	s_waitcnt vmcnt(8)
	s_waitcnt lgkmcnt(0)
	s_barrier
; #define PG8_STAGE(bufoff, gbase, voff) do { _Pragma("unroll") for (int _i = 0; _i < 2; ++_i) \
;         __builtin_amdgcn_global_load_lds((const unsigned*)((const char*)(gbase) + (voff)[_i]), (PG8_LAS unsigned*)(lds + (bufoff) + ldsw + _i * 8192), 16, 0, 0); } while (0)
; #define PG8_LDA(dst, b, h) do { _Pragma("unroll") for (int m = 0; m < 4; ++m) _Pragma("unroll") for (int k = 0; k < 2; ++k) dst[m][k] = *(const PG8_LAS bf16x8*)(lds + PG8_SA(b, h) + aoff + m * 2048 + k * 1024); } while (0)
; #define PG8_LDB(dst, b, h) do { _Pragma("unroll") for (int n = 0; n < 2; ++n) _Pragma("unroll") for (int k = 0; k < 2; ++k) dst[n][k] = *(const PG8_LAS bf16x8*)(lds + PG8_SB(b, h) + boff + n * 2048 + k * 1024); } while (0)
; #define PG8_MMA(ai, bj, At, Bt) do { __builtin_amdgcn_s_setprio(1); _Pragma("unroll") for (int m = 0; m < 4; ++m) _Pragma("unroll") for (int n = 0; n < 2; ++n) _Pragma("unroll") for (int k = 0; k < 2; ++k) \
;         acc[ai][bj][m][n] = __builtin_amdgcn_mfma_f32_16x16x32_bf16(Bt[n][k], At[m][k], acc[ai][bj][m][n], 0, 0, 0); __builtin_amdgcn_s_setprio(0); } while (0)
; #define PG8_WAIT_V(n) asm volatile("s_waitcnt vmcnt(" #n ")" ::: "memory")
; #define PG8_WAIT_L(n) asm volatile("s_waitcnt lgkmcnt(" #n ")" ::: "memory")
; #define PG8_BAR __builtin_amdgcn_s_barrier()
; #define PG8_SCHED __builtin_amdgcn_sched_barrier(0)
; template <class Epi, class Sched, bool ALIGN_EPI = false, bool SP2 = false>
; __device__ __forceinline__ void gemm_phase(PG8_LAS unsigned char* lds, const Gemm g, const Sched& S, const Epi& E) {
;     ...
;             PG8_WAIT_V(8); PG8_WAIT_L(0); PG8_BAR; PG8_MMA(1, 0, At, B0); PG8_MMA(1, 1, At, B1); PG8_BAR; PG8_SCHED;
;             PG8_LDB(B0, 1, 0); PG8_LDB(B1, 1, 1); PG8_SCHED; PG8_LDA(At, 1, 0); PG8_STAGE(PG8_SA(0, 1), a2 + hstepB, voffA);
;             PG8_WAIT_V(8); PG8_WAIT_L(0); PG8_BAR; PG8_MMA(0, 0, At, B0); PG8_MMA(0, 1, At, B1); PG8_BAR; PG8_SCHED;
;             PG8_LDA(At, 1, 1); PG8_STAGE(PG8_SB(1, 0), b3, voffB); PG8_STAGE(PG8_SB(1, 1), b3 + hstepB, voffB); PG8_STAGE(PG8_SA(1, 0), a3, voffA);
	s_setprio 1
	s_waitcnt lgkmcnt(0)
	v_mfma_f32_16x16x32_bf16 v[60:63], v[128:131], v[182:185], v[60:63]
	v_mfma_f32_16x16x32_bf16 v[60:63], v[132:135], v[186:189], v[60:63]
	v_mfma_f32_16x16x32_bf16 v[52:55], v[152:155], v[182:185], v[52:55]
	v_mfma_f32_16x16x32_bf16 v[52:55], v[156:159], v[186:189], v[52:55]
	v_mfma_f32_16x16x32_bf16 v[44:47], v[128:131], v[190:193], v[44:47]
	v_mfma_f32_16x16x32_bf16 v[44:47], v[132:135], v[194:197], v[44:47]
	v_mfma_f32_16x16x32_bf16 v[36:39], v[152:155], v[190:193], v[36:39]
	v_mfma_f32_16x16x32_bf16 v[36:39], v[156:159], v[194:197], v[36:39]
	v_mfma_f32_16x16x32_bf16 v[28:31], v[128:131], v[198:201], v[28:31]
	v_mfma_f32_16x16x32_bf16 v[28:31], v[132:135], v[202:205], v[28:31]
	v_mfma_f32_16x16x32_bf16 v[20:23], v[152:155], v[198:201], v[20:23]
	v_mfma_f32_16x16x32_bf16 v[20:23], v[156:159], v[202:205], v[20:23]
	v_mfma_f32_16x16x32_bf16 v[12:15], v[128:131], v[206:209], v[12:15]
	v_mfma_f32_16x16x32_bf16 v[12:15], v[132:135], v[210:213], v[12:15]
	v_mfma_f32_16x16x32_bf16 v[4:7], v[152:155], v[206:209], v[4:7]
	v_mfma_f32_16x16x32_bf16 v[4:7], v[156:159], v[210:213], v[4:7]
	s_setprio 0
	s_setprio 1
	v_mfma_f32_16x16x32_bf16 v[56:59], v[160:163], v[182:185], v[56:59]
	v_mfma_f32_16x16x32_bf16 v[56:59], v[170:173], v[186:189], v[56:59]
	v_mfma_f32_16x16x32_bf16 v[48:51], v[174:177], v[182:185], v[48:51]
	v_mfma_f32_16x16x32_bf16 v[48:51], v[178:181], v[186:189], v[48:51]
	v_mfma_f32_16x16x32_bf16 v[40:43], v[160:163], v[190:193], v[40:43]
	v_mfma_f32_16x16x32_bf16 v[40:43], v[170:173], v[194:197], v[40:43]
	v_mfma_f32_16x16x32_bf16 v[32:35], v[174:177], v[190:193], v[32:35]
	v_mfma_f32_16x16x32_bf16 v[32:35], v[178:181], v[194:197], v[32:35]
	v_mfma_f32_16x16x32_bf16 v[24:27], v[160:163], v[198:201], v[24:27]
	v_mfma_f32_16x16x32_bf16 v[24:27], v[170:173], v[202:205], v[24:27]
	v_mfma_f32_16x16x32_bf16 v[16:19], v[174:177], v[198:201], v[16:19]
	v_mfma_f32_16x16x32_bf16 v[16:19], v[178:181], v[202:205], v[16:19]
	s_setprio 2
	s_barrier
	v_mfma_f32_16x16x32_bf16 v[8:11], v[160:163], v[206:209], v[8:11]
	v_mfma_f32_16x16x32_bf16 v[8:11], v[170:173], v[210:213], v[8:11]
	v_mfma_f32_16x16x32_bf16 v[0:3], v[174:177], v[206:209], v[0:3]
	v_mfma_f32_16x16x32_bf16 v[0:3], v[178:181], v[210:213], v[0:3]
	s_setprio 0
	s_add_i32 s63, 0, 0x18000
	v_add_u32_e32 v151, s63, v165
	s_add_i32 s66, 0, 0x1c000
	ds_read_b128 v[128:131], v151
	ds_read_b128 v[132:135], v151 offset:1024
	ds_read_b128 v[152:155], v151 offset:2048
	ds_read_b128 v[156:159], v151 offset:3072
	v_add_u32_e32 v151, s66, v165
	ds_read_b128 v[160:163], v151
	ds_read_b128 v[170:173], v151 offset:1024
	ds_read_b128 v[174:177], v151 offset:2048
	ds_read_b128 v[178:181], v151 offset:3072
	s_add_u32 s42, s42, 0x4000
	s_addc_u32 s43, s43, 0
	s_mov_b32 m0, s21
	v_lshl_add_u64 v[214:215], s[42:43], 0, v[142:143]
	ds_read_b128 v[182:185], v168 offset:32768
	ds_read_b128 v[186:189], v168 offset:33792
	ds_read_b128 v[190:193], v168 offset:34816
	ds_read_b128 v[194:197], v168 offset:35840
	ds_read_b128 v[198:201], v168 offset:36864
	ds_read_b128 v[202:205], v168 offset:37888
	ds_read_b128 v[206:209], v168 offset:38912
	ds_read_b128 v[210:213], v168 offset:39936
	global_load_lds_dwordx4 v[214:215], off
	v_lshl_add_u64 v[214:215], s[42:43], 0, v[138:139]
	s_mov_b32 m0, s22
	s_nop 0
	global_load_lds_dwordx4 v[214:215], off
	s_waitcnt vmcnt(8)
	s_waitcnt lgkmcnt(0)
	s_barrier
	s_setprio 1
	s_waitcnt lgkmcnt(0)
	v_mfma_f32_16x16x32_bf16 v[124:127], v[128:131], v[182:185], v[124:127]
	v_mfma_f32_16x16x32_bf16 v[124:127], v[132:135], v[186:189], v[124:127]
	v_mfma_f32_16x16x32_bf16 v[116:119], v[152:155], v[182:185], v[116:119]
	v_mfma_f32_16x16x32_bf16 v[116:119], v[156:159], v[186:189], v[116:119]
	v_mfma_f32_16x16x32_bf16 v[108:111], v[128:131], v[190:193], v[108:111]
	v_mfma_f32_16x16x32_bf16 v[108:111], v[132:135], v[194:197], v[108:111]
	v_mfma_f32_16x16x32_bf16 v[100:103], v[152:155], v[190:193], v[100:103]
	v_mfma_f32_16x16x32_bf16 v[100:103], v[156:159], v[194:197], v[100:103]
	v_mfma_f32_16x16x32_bf16 v[92:95], v[128:131], v[198:201], v[92:95]
	v_mfma_f32_16x16x32_bf16 v[92:95], v[132:135], v[202:205], v[92:95]
	v_mfma_f32_16x16x32_bf16 v[84:87], v[152:155], v[198:201], v[84:87]
	v_mfma_f32_16x16x32_bf16 v[84:87], v[156:159], v[202:205], v[84:87]
	v_mfma_f32_16x16x32_bf16 v[76:79], v[128:131], v[206:209], v[76:79]
	v_mfma_f32_16x16x32_bf16 v[76:79], v[132:135], v[210:213], v[76:79]
	v_mfma_f32_16x16x32_bf16 v[68:71], v[152:155], v[206:209], v[68:71]
	v_mfma_f32_16x16x32_bf16 v[68:71], v[156:159], v[210:213], v[68:71]
	s_setprio 0
	s_setprio 1
	v_mfma_f32_16x16x32_bf16 v[120:123], v[160:163], v[182:185], v[120:123]
	v_mfma_f32_16x16x32_bf16 v[120:123], v[170:173], v[186:189], v[120:123]
	v_mfma_f32_16x16x32_bf16 v[112:115], v[174:177], v[182:185], v[112:115]
	v_mfma_f32_16x16x32_bf16 v[112:115], v[178:181], v[186:189], v[112:115]
	v_mfma_f32_16x16x32_bf16 v[104:107], v[160:163], v[190:193], v[104:107]
	v_mfma_f32_16x16x32_bf16 v[104:107], v[170:173], v[194:197], v[104:107]
	v_mfma_f32_16x16x32_bf16 v[96:99], v[174:177], v[190:193], v[96:99]
	v_mfma_f32_16x16x32_bf16 v[96:99], v[178:181], v[194:197], v[96:99]
	v_mfma_f32_16x16x32_bf16 v[88:91], v[160:163], v[198:201], v[88:91]
	v_mfma_f32_16x16x32_bf16 v[88:91], v[170:173], v[202:205], v[88:91]
	v_mfma_f32_16x16x32_bf16 v[80:83], v[174:177], v[198:201], v[80:83]
	v_mfma_f32_16x16x32_bf16 v[80:83], v[178:181], v[202:205], v[80:83]
	s_setprio 2
	s_barrier
; #define PG8_STAGE(bufoff, gbase, voff) do { _Pragma("unroll") for (int _i = 0; _i < 2; ++_i) \
;         __builtin_amdgcn_global_load_lds((const unsigned*)((const char*)(gbase) + (voff)[_i]), (PG8_LAS unsigned*)(lds + (bufoff) + ldsw + _i * 8192), 16, 0, 0); } while (0)
; #define PG8_LDA(dst, b, h) do { _Pragma("unroll") for (int m = 0; m < 4; ++m) _Pragma("unroll") for (int k = 0; k < 2; ++k) dst[m][k] = *(const PG8_LAS bf16x8*)(lds + PG8_SA(b, h) + aoff + m * 2048 + k * 1024); } while (0)
; #define PG8_MMA(ai, bj, At, Bt) do { __builtin_amdgcn_s_setprio(1); _Pragma("unroll") for (int m = 0; m < 4; ++m) _Pragma("unroll") for (int n = 0; n < 2; ++n) _Pragma("unroll") for (int k = 0; k < 2; ++k) \
;         acc[ai][bj][m][n] = __builtin_amdgcn_mfma_f32_16x16x32_bf16(Bt[n][k], At[m][k], acc[ai][bj][m][n], 0, 0, 0); __builtin_amdgcn_s_setprio(0); } while (0)
; #define PG8_WAIT_V(n) asm volatile("s_waitcnt vmcnt(" #n ")" ::: "memory")
; #define PG8_WAIT_L(n) asm volatile("s_waitcnt lgkmcnt(" #n ")" ::: "memory")
; #define PG8_BAR __builtin_amdgcn_s_barrier()
; #define PG8_SCHED __builtin_amdgcn_sched_barrier(0)
; template <class Epi, class Sched, bool ALIGN_EPI = false, bool SP2 = false>
; __device__ __forceinline__ void gemm_phase(PG8_LAS unsigned char* lds, const Gemm g, const Sched& S, const Epi& E) {
;     ...
;             PG8_LDA(At, 1, 1); PG8_STAGE(PG8_SB(1, 0), b3, voffB); PG8_STAGE(PG8_SB(1, 1), b3 + hstepB, voffB); PG8_STAGE(PG8_SA(1, 0), a3, voffA);
;             PG8_WAIT_V(8); PG8_WAIT_L(0); PG8_BAR; PG8_MMA(1, 0, At, B0); PG8_MMA(1, 1, At, B1); PG8_BAR; PG8_SCHED;
	v_mfma_f32_16x16x32_bf16 v[72:75], v[160:163], v[206:209], v[72:75]
	v_mfma_f32_16x16x32_bf16 v[72:75], v[170:173], v[210:213], v[72:75]
	v_mfma_f32_16x16x32_bf16 v[64:67], v[174:177], v[206:209], v[64:67]
	v_mfma_f32_16x16x32_bf16 v[64:67], v[178:181], v[210:213], v[64:67]
	s_setprio 0
	s_add_u32 s42, s40, 0x8000
	s_addc_u32 s43, s41, 0
	s_add_i32 s63, s63, s16
	v_lshl_add_u64 v[214:215], s[42:43], 0, v[140:141]
	s_mov_b32 m0, s63
	ds_read_b128 v[182:185], v168 offset:49152
	ds_read_b128 v[186:189], v168 offset:50176
	ds_read_b128 v[190:193], v168 offset:51200
	ds_read_b128 v[194:197], v168 offset:52224
	ds_read_b128 v[198:201], v168 offset:53248
	ds_read_b128 v[202:205], v168 offset:54272
	ds_read_b128 v[206:209], v168 offset:55296
	ds_read_b128 v[210:213], v168 offset:56320
	global_load_lds_dwordx4 v[214:215], off
	s_add_i32 m0, s63, 0x2000
	s_add_u32 s40, s40, 0xc000
	v_lshl_add_u64 v[214:215], s[42:43], 0, v[136:137]
	s_addc_u32 s41, s41, 0
	s_add_i32 s42, s66, s16
	global_load_lds_dwordx4 v[214:215], off
	v_lshl_add_u64 v[214:215], s[40:41], 0, v[140:141]
	s_mov_b32 m0, s42
	s_nop 0
	global_load_lds_dwordx4 v[214:215], off
	v_lshl_add_u64 v[214:215], s[40:41], 0, v[136:137]
	s_add_i32 m0, s42, 0x2000
	s_nop 0
	global_load_lds_dwordx4 v[214:215], off
	v_lshl_add_u64 v[214:215], s[38:39], 0, v[142:143]
	s_mov_b32 m0, s25
	s_nop 0
	global_load_lds_dwordx4 v[214:215], off
	v_lshl_add_u64 v[214:215], s[38:39], 0, v[138:139]
	s_mov_b32 m0, s26
	s_nop 0
	global_load_lds_dwordx4 v[214:215], off
	s_waitcnt vmcnt(8)
	s_waitcnt lgkmcnt(0)
	s_barrier
	s_setprio 1
	s_waitcnt lgkmcnt(0)
	v_mfma_f32_16x16x32_bf16 v[60:63], v[128:131], v[182:185], v[60:63]
	v_mfma_f32_16x16x32_bf16 v[60:63], v[132:135], v[186:189], v[60:63]
	v_mfma_f32_16x16x32_bf16 v[52:55], v[152:155], v[182:185], v[52:55]
	v_mfma_f32_16x16x32_bf16 v[52:55], v[156:159], v[186:189], v[52:55]
	v_mfma_f32_16x16x32_bf16 v[44:47], v[128:131], v[190:193], v[44:47]
	v_mfma_f32_16x16x32_bf16 v[44:47], v[132:135], v[194:197], v[44:47]
	v_mfma_f32_16x16x32_bf16 v[36:39], v[152:155], v[190:193], v[36:39]
	v_mfma_f32_16x16x32_bf16 v[36:39], v[156:159], v[194:197], v[36:39]
	v_mfma_f32_16x16x32_bf16 v[28:31], v[128:131], v[198:201], v[28:31]
	v_mfma_f32_16x16x32_bf16 v[28:31], v[132:135], v[202:205], v[28:31]
	v_mfma_f32_16x16x32_bf16 v[20:23], v[152:155], v[198:201], v[20:23]
	v_mfma_f32_16x16x32_bf16 v[20:23], v[156:159], v[202:205], v[20:23]
	v_mfma_f32_16x16x32_bf16 v[12:15], v[128:131], v[206:209], v[12:15]
	v_mfma_f32_16x16x32_bf16 v[12:15], v[132:135], v[210:213], v[12:15]
	v_mfma_f32_16x16x32_bf16 v[4:7], v[152:155], v[206:209], v[4:7]
	v_mfma_f32_16x16x32_bf16 v[4:7], v[156:159], v[210:213], v[4:7]
	s_setprio 0
	s_setprio 1
	v_mfma_f32_16x16x32_bf16 v[56:59], v[160:163], v[182:185], v[56:59]
	v_mfma_f32_16x16x32_bf16 v[56:59], v[170:173], v[186:189], v[56:59]
	v_mfma_f32_16x16x32_bf16 v[48:51], v[174:177], v[182:185], v[48:51]
	v_mfma_f32_16x16x32_bf16 v[48:51], v[178:181], v[186:189], v[48:51]
	v_mfma_f32_16x16x32_bf16 v[40:43], v[160:163], v[190:193], v[40:43]
	v_mfma_f32_16x16x32_bf16 v[40:43], v[170:173], v[194:197], v[40:43]
	v_mfma_f32_16x16x32_bf16 v[32:35], v[174:177], v[190:193], v[32:35]
	v_mfma_f32_16x16x32_bf16 v[32:35], v[178:181], v[194:197], v[32:35]
	v_mfma_f32_16x16x32_bf16 v[24:27], v[160:163], v[198:201], v[24:27]
	v_mfma_f32_16x16x32_bf16 v[24:27], v[170:173], v[202:205], v[24:27]
	v_mfma_f32_16x16x32_bf16 v[16:19], v[174:177], v[198:201], v[16:19]
	v_mfma_f32_16x16x32_bf16 v[16:19], v[178:181], v[202:205], v[16:19]
	s_setprio 2
	s_barrier
	v_mfma_f32_16x16x32_bf16 v[8:11], v[160:163], v[206:209], v[8:11]
	v_mfma_f32_16x16x32_bf16 v[8:11], v[170:173], v[210:213], v[8:11]
	v_mfma_f32_16x16x32_bf16 v[0:3], v[174:177], v[206:209], v[0:3]
	v_mfma_f32_16x16x32_bf16 v[0:3], v[178:181], v[210:213], v[0:3]
	s_setprio 0
	s_add_i32 s62, s62, 2
	s_add_u32 s36, s36, 0x10000
	s_addc_u32 s37, s37, 0
	s_add_u32 s44, s44, 0x10000
	s_addc_u32 s45, s45, 0
	s_cmp_gt_u32 s62, 29
	s_cbranch_scc0 .LBB0_263
	s_and_b64 vcc, exec, s[8:9]
	s_cbranch_vccz .LBB0_266
	s_barrier
